# code placement: s_nop padding so every 8-byte vector/LDS/memory instruction in the seven GEMM K-loops starts 8-byte aligned
# speedup vs baseline: 1.0185x; 1.0025x over previous
.Lg2_p2_loop:
	ds_read_b128 v[208:211], v172 offset:8192
	ds_read_b128 v[212:215], v172 offset:10240
	ds_read_b128 v[218:221], v172 offset:12288
	ds_read_b128 v[224:227], v172 offset:14336
	s_waitcnt lgkmcnt(4)
	s_nop 0
	v_mfma_f32_16x16x32_bf16 v[126:129], v[228:231], v[192:195], v[126:129]
	v_mfma_f32_16x16x32_bf16 v[122:125], v[232:235], v[192:195], v[122:125]
	v_mfma_f32_16x16x32_bf16 v[118:121], v[236:239], v[192:195], v[118:121]
	v_mfma_f32_16x16x32_bf16 v[114:117], v[240:243], v[192:195], v[114:117]
	v_mfma_f32_16x16x32_bf16 v[110:113], v[228:231], v[196:199], v[110:113]
	v_mfma_f32_16x16x32_bf16 v[106:109], v[232:235], v[196:199], v[106:109]
	v_mfma_f32_16x16x32_bf16 v[102:105], v[236:239], v[196:199], v[102:105]
	v_mfma_f32_16x16x32_bf16 v[98:101], v[240:243], v[196:199], v[98:101]
	v_mfma_f32_16x16x32_bf16 v[94:97], v[228:231], v[200:203], v[94:97]
	v_mfma_f32_16x16x32_bf16 v[90:93], v[232:235], v[200:203], v[90:93]
	v_mfma_f32_16x16x32_bf16 v[86:89], v[236:239], v[200:203], v[86:89]
	v_mfma_f32_16x16x32_bf16 v[82:85], v[240:243], v[200:203], v[82:85]
	v_mfma_f32_16x16x32_bf16 v[78:81], v[228:231], v[204:207], v[78:81]
	v_mfma_f32_16x16x32_bf16 v[74:77], v[232:235], v[204:207], v[74:77]
	v_mfma_f32_16x16x32_bf16 v[70:73], v[236:239], v[204:207], v[70:73]
	v_mfma_f32_16x16x32_bf16 v[66:69], v[240:243], v[204:207], v[66:69]
	ds_read_b128 v[192:195], v216
	ds_read_b128 v[196:199], v216 offset:2048
	ds_read_b128 v[200:203], v216 offset:4096
	ds_read_b128 v[204:207], v216 offset:6144
	ds_read_b128 v[244:247], v217
	ds_read_b128 v[248:251], v217 offset:2048
	ds_read_b128 v[252:255], v217 offset:4096
	ds_read_b128 v[152:155], v217 offset:6144
	s_waitcnt lgkmcnt(8)
	s_nop 0
	v_mfma_f32_16x16x32_bf16 v[62:65], v[228:231], v[208:211], v[62:65]
	v_mfma_f32_16x16x32_bf16 v[58:61], v[232:235], v[208:211], v[58:61]
	v_mfma_f32_16x16x32_bf16 v[54:57], v[236:239], v[208:211], v[54:57]
	v_mfma_f32_16x16x32_bf16 v[50:53], v[240:243], v[208:211], v[50:53]
	v_mfma_f32_16x16x32_bf16 v[46:49], v[228:231], v[212:215], v[46:49]
	v_mfma_f32_16x16x32_bf16 v[42:45], v[232:235], v[212:215], v[42:45]
	v_mfma_f32_16x16x32_bf16 v[38:41], v[236:239], v[212:215], v[38:41]
	v_mfma_f32_16x16x32_bf16 v[34:37], v[240:243], v[212:215], v[34:37]
	v_mfma_f32_16x16x32_bf16 v[30:33], v[228:231], v[218:221], v[30:33]
	v_mfma_f32_16x16x32_bf16 v[26:29], v[232:235], v[218:221], v[26:29]
	v_mfma_f32_16x16x32_bf16 v[22:25], v[236:239], v[218:221], v[22:25]
	v_mfma_f32_16x16x32_bf16 v[18:21], v[240:243], v[218:221], v[18:21]
	v_mfma_f32_16x16x32_bf16 v[14:17], v[228:231], v[224:227], v[14:17]
	v_mfma_f32_16x16x32_bf16 v[10:13], v[232:235], v[224:227], v[10:13]
	v_mfma_f32_16x16x32_bf16 v[6:9], v[236:239], v[224:227], v[6:9]
	v_mfma_f32_16x16x32_bf16 v[2:5], v[240:243], v[224:227], v[2:5]
	ds_read_b128 v[208:211], v216 offset:8192
	ds_read_b128 v[212:215], v216 offset:10240
	ds_read_b128 v[218:221], v216 offset:12288
	ds_read_b128 v[224:227], v216 offset:14336
	s_waitcnt lgkmcnt(4)
	s_nop 0
	v_mfma_f32_16x16x32_bf16 v[126:129], v[244:247], v[192:195], v[126:129]
	v_mfma_f32_16x16x32_bf16 v[122:125], v[248:251], v[192:195], v[122:125]
	v_mfma_f32_16x16x32_bf16 v[118:121], v[252:255], v[192:195], v[118:121]
	v_mfma_f32_16x16x32_bf16 v[114:117], v[152:155], v[192:195], v[114:117]
	v_mfma_f32_16x16x32_bf16 v[110:113], v[244:247], v[196:199], v[110:113]
	v_mfma_f32_16x16x32_bf16 v[106:109], v[248:251], v[196:199], v[106:109]
	v_mfma_f32_16x16x32_bf16 v[102:105], v[252:255], v[196:199], v[102:105]
	v_mfma_f32_16x16x32_bf16 v[98:101], v[152:155], v[196:199], v[98:101]
	v_mfma_f32_16x16x32_bf16 v[94:97], v[244:247], v[200:203], v[94:97]
	v_mfma_f32_16x16x32_bf16 v[90:93], v[248:251], v[200:203], v[90:93]
	v_mfma_f32_16x16x32_bf16 v[86:89], v[252:255], v[200:203], v[86:89]
	v_mfma_f32_16x16x32_bf16 v[82:85], v[152:155], v[200:203], v[82:85]
	v_mfma_f32_16x16x32_bf16 v[78:81], v[244:247], v[204:207], v[78:81]
	v_mfma_f32_16x16x32_bf16 v[74:77], v[248:251], v[204:207], v[74:77]
	v_mfma_f32_16x16x32_bf16 v[70:73], v[252:255], v[204:207], v[70:73]
	v_mfma_f32_16x16x32_bf16 v[66:69], v[152:155], v[204:207], v[66:69]
	s_waitcnt vmcnt(0)
	s_waitcnt lgkmcnt(0)
	s_barrier
	s_add_u32 s0, s0, 0x80
	s_addc_u32 s1, s1, 0
	s_add_u32 s98, s98, 0x80
	s_addc_u32 s99, s99, 0
	s_add_u32 s100, s100, 0x80
	s_addc_u32 s101, s101, 0
	s_cmpk_eq_i32 s0, 0x780
	s_cbranch_scc1 .Lg2_p2_tail
	ds_read_b128 v[192:195], v172 offset:32768
	ds_read_b128 v[196:199], v172 offset:34816
	ds_read_b128 v[200:203], v172 offset:36864
	ds_read_b128 v[204:207], v172 offset:38912
	ds_read_b128 v[228:231], v173 offset:32768
	ds_read_b128 v[232:235], v173 offset:34816
	ds_read_b128 v[236:239], v173 offset:36864
	ds_read_b128 v[240:243], v173 offset:38912
	v_mfma_f32_16x16x32_bf16 v[62:65], v[244:247], v[208:211], v[62:65]
	s_mov_b32 m0, s96
	s_nop 0
	v_mfma_f32_16x16x32_bf16 v[58:61], v[248:251], v[208:211], v[58:61]
	global_load_lds_dwordx4 v160, s[98:99]
	v_mfma_f32_16x16x32_bf16 v[54:57], v[252:255], v[208:211], v[54:57]
	s_add_u32 m0, m0, 0x2000
	v_mfma_f32_16x16x32_bf16 v[50:53], v[152:155], v[208:211], v[50:53]
	global_load_lds_dwordx4 v161, s[98:99]
	v_mfma_f32_16x16x32_bf16 v[46:49], v[244:247], v[212:215], v[46:49]
	s_add_u32 m0, m0, 0x2000
	v_mfma_f32_16x16x32_bf16 v[42:45], v[248:251], v[212:215], v[42:45]
	global_load_lds_dwordx4 v162, s[98:99]
	v_mfma_f32_16x16x32_bf16 v[38:41], v[252:255], v[212:215], v[38:41]
	s_add_u32 m0, m0, 0x2000
	v_mfma_f32_16x16x32_bf16 v[34:37], v[152:155], v[212:215], v[34:37]
	global_load_lds_dwordx4 v163, s[98:99]
	v_mfma_f32_16x16x32_bf16 v[30:33], v[244:247], v[218:221], v[30:33]
	s_add_u32 m0, m0, 0xa000
	v_mfma_f32_16x16x32_bf16 v[26:29], v[248:251], v[218:221], v[26:29]
	global_load_lds_dwordx4 v164, s[100:101]
	v_mfma_f32_16x16x32_bf16 v[22:25], v[252:255], v[218:221], v[22:25]
	s_add_u32 m0, m0, 0x2000
	v_mfma_f32_16x16x32_bf16 v[18:21], v[152:155], v[218:221], v[18:21]
	global_load_lds_dwordx4 v165, s[100:101]
	v_mfma_f32_16x16x32_bf16 v[14:17], v[244:247], v[224:227], v[14:17]
	s_add_u32 m0, m0, 0x2000
	v_mfma_f32_16x16x32_bf16 v[10:13], v[248:251], v[224:227], v[10:13]
	global_load_lds_dwordx4 v166, s[100:101]
	v_mfma_f32_16x16x32_bf16 v[6:9], v[252:255], v[224:227], v[6:9]
	s_add_u32 m0, m0, 0x2000
	v_mfma_f32_16x16x32_bf16 v[2:5], v[152:155], v[224:227], v[2:5]
	global_load_lds_dwordx4 v167, s[100:101]
	ds_read_b128 v[208:211], v172 offset:40960
	ds_read_b128 v[212:215], v172 offset:43008
	ds_read_b128 v[218:221], v172 offset:45056
	ds_read_b128 v[224:227], v172 offset:47104
	s_waitcnt lgkmcnt(4)
	s_nop 0
	v_mfma_f32_16x16x32_bf16 v[126:129], v[228:231], v[192:195], v[126:129]
	v_mfma_f32_16x16x32_bf16 v[122:125], v[232:235], v[192:195], v[122:125]
	v_mfma_f32_16x16x32_bf16 v[118:121], v[236:239], v[192:195], v[118:121]
	v_mfma_f32_16x16x32_bf16 v[114:117], v[240:243], v[192:195], v[114:117]
	v_mfma_f32_16x16x32_bf16 v[110:113], v[228:231], v[196:199], v[110:113]
	v_mfma_f32_16x16x32_bf16 v[106:109], v[232:235], v[196:199], v[106:109]
	v_mfma_f32_16x16x32_bf16 v[102:105], v[236:239], v[196:199], v[102:105]
	v_mfma_f32_16x16x32_bf16 v[98:101], v[240:243], v[196:199], v[98:101]
	v_mfma_f32_16x16x32_bf16 v[94:97], v[228:231], v[200:203], v[94:97]
	v_mfma_f32_16x16x32_bf16 v[90:93], v[232:235], v[200:203], v[90:93]
	v_mfma_f32_16x16x32_bf16 v[86:89], v[236:239], v[200:203], v[86:89]
	v_mfma_f32_16x16x32_bf16 v[82:85], v[240:243], v[200:203], v[82:85]
	v_mfma_f32_16x16x32_bf16 v[78:81], v[228:231], v[204:207], v[78:81]
	v_mfma_f32_16x16x32_bf16 v[74:77], v[232:235], v[204:207], v[74:77]
	v_mfma_f32_16x16x32_bf16 v[70:73], v[236:239], v[204:207], v[70:73]
	v_mfma_f32_16x16x32_bf16 v[66:69], v[240:243], v[204:207], v[66:69]
	ds_read_b128 v[192:195], v216 offset:32768
	ds_read_b128 v[196:199], v216 offset:34816
	ds_read_b128 v[200:203], v216 offset:36864
	ds_read_b128 v[204:207], v216 offset:38912
	ds_read_b128 v[244:247], v217 offset:32768
	ds_read_b128 v[248:251], v217 offset:34816
	ds_read_b128 v[252:255], v217 offset:36864
	ds_read_b128 v[152:155], v217 offset:38912
	s_waitcnt lgkmcnt(8)
	s_nop 0
	v_mfma_f32_16x16x32_bf16 v[62:65], v[228:231], v[208:211], v[62:65]
	v_mfma_f32_16x16x32_bf16 v[58:61], v[232:235], v[208:211], v[58:61]
	v_mfma_f32_16x16x32_bf16 v[54:57], v[236:239], v[208:211], v[54:57]
	v_mfma_f32_16x16x32_bf16 v[50:53], v[240:243], v[208:211], v[50:53]
	v_mfma_f32_16x16x32_bf16 v[46:49], v[228:231], v[212:215], v[46:49]
	v_mfma_f32_16x16x32_bf16 v[42:45], v[232:235], v[212:215], v[42:45]
	v_mfma_f32_16x16x32_bf16 v[38:41], v[236:239], v[212:215], v[38:41]
	v_mfma_f32_16x16x32_bf16 v[34:37], v[240:243], v[212:215], v[34:37]
	v_mfma_f32_16x16x32_bf16 v[30:33], v[228:231], v[218:221], v[30:33]
	v_mfma_f32_16x16x32_bf16 v[26:29], v[232:235], v[218:221], v[26:29]
	v_mfma_f32_16x16x32_bf16 v[22:25], v[236:239], v[218:221], v[22:25]
	v_mfma_f32_16x16x32_bf16 v[18:21], v[240:243], v[218:221], v[18:21]
	v_mfma_f32_16x16x32_bf16 v[14:17], v[228:231], v[224:227], v[14:17]
	v_mfma_f32_16x16x32_bf16 v[10:13], v[232:235], v[224:227], v[10:13]
	v_mfma_f32_16x16x32_bf16 v[6:9], v[236:239], v[224:227], v[6:9]
	v_mfma_f32_16x16x32_bf16 v[2:5], v[240:243], v[224:227], v[2:5]
	ds_read_b128 v[208:211], v216 offset:40960
	ds_read_b128 v[212:215], v216 offset:43008
	ds_read_b128 v[218:221], v216 offset:45056
	ds_read_b128 v[224:227], v216 offset:47104
	s_waitcnt lgkmcnt(4)
	s_nop 0
	v_mfma_f32_16x16x32_bf16 v[126:129], v[244:247], v[192:195], v[126:129]
	v_mfma_f32_16x16x32_bf16 v[122:125], v[248:251], v[192:195], v[122:125]
	v_mfma_f32_16x16x32_bf16 v[118:121], v[252:255], v[192:195], v[118:121]
	v_mfma_f32_16x16x32_bf16 v[114:117], v[152:155], v[192:195], v[114:117]
	v_mfma_f32_16x16x32_bf16 v[110:113], v[244:247], v[196:199], v[110:113]
	v_mfma_f32_16x16x32_bf16 v[106:109], v[248:251], v[196:199], v[106:109]
	v_mfma_f32_16x16x32_bf16 v[102:105], v[252:255], v[196:199], v[102:105]
	v_mfma_f32_16x16x32_bf16 v[98:101], v[152:155], v[196:199], v[98:101]
	v_mfma_f32_16x16x32_bf16 v[94:97], v[244:247], v[200:203], v[94:97]
	v_mfma_f32_16x16x32_bf16 v[90:93], v[248:251], v[200:203], v[90:93]
	v_mfma_f32_16x16x32_bf16 v[86:89], v[252:255], v[200:203], v[86:89]
	v_mfma_f32_16x16x32_bf16 v[82:85], v[152:155], v[200:203], v[82:85]
	v_mfma_f32_16x16x32_bf16 v[78:81], v[244:247], v[204:207], v[78:81]
	v_mfma_f32_16x16x32_bf16 v[74:77], v[248:251], v[204:207], v[74:77]
	v_mfma_f32_16x16x32_bf16 v[70:73], v[252:255], v[204:207], v[70:73]
	v_mfma_f32_16x16x32_bf16 v[66:69], v[152:155], v[204:207], v[66:69]
	s_waitcnt vmcnt(0)
	s_waitcnt lgkmcnt(0)
	s_barrier
	s_add_u32 s0, s0, 0x80
	s_addc_u32 s1, s1, 0
	s_add_u32 s98, s98, 0x80
	s_addc_u32 s99, s99, 0
	s_add_u32 s100, s100, 0x80
	s_addc_u32 s101, s101, 0
	s_cmpk_eq_i32 s0, 0x780
	s_cbranch_scc1 .Lg2_p2_tail
	ds_read_b128 v[192:195], v172
	ds_read_b128 v[196:199], v172 offset:2048
	ds_read_b128 v[200:203], v172 offset:4096
	ds_read_b128 v[204:207], v172 offset:6144
	ds_read_b128 v[228:231], v173
	ds_read_b128 v[232:235], v173 offset:2048
	ds_read_b128 v[236:239], v173 offset:4096
	ds_read_b128 v[240:243], v173 offset:6144
	v_mfma_f32_16x16x32_bf16 v[62:65], v[244:247], v[208:211], v[62:65]
	s_add_u32 m0, s96, 0x8000
	v_mfma_f32_16x16x32_bf16 v[58:61], v[248:251], v[208:211], v[58:61]
	global_load_lds_dwordx4 v160, s[98:99]
	v_mfma_f32_16x16x32_bf16 v[54:57], v[252:255], v[208:211], v[54:57]
	s_add_u32 m0, m0, 0x2000
	v_mfma_f32_16x16x32_bf16 v[50:53], v[152:155], v[208:211], v[50:53]
	global_load_lds_dwordx4 v161, s[98:99]
	v_mfma_f32_16x16x32_bf16 v[46:49], v[244:247], v[212:215], v[46:49]
	s_add_u32 m0, m0, 0x2000
	v_mfma_f32_16x16x32_bf16 v[42:45], v[248:251], v[212:215], v[42:45]
	global_load_lds_dwordx4 v162, s[98:99]
	v_mfma_f32_16x16x32_bf16 v[38:41], v[252:255], v[212:215], v[38:41]
	s_add_u32 m0, m0, 0x2000
	v_mfma_f32_16x16x32_bf16 v[34:37], v[152:155], v[212:215], v[34:37]
	global_load_lds_dwordx4 v163, s[98:99]
	v_mfma_f32_16x16x32_bf16 v[30:33], v[244:247], v[218:221], v[30:33]
	s_add_u32 m0, m0, 0xa000
	v_mfma_f32_16x16x32_bf16 v[26:29], v[248:251], v[218:221], v[26:29]
	global_load_lds_dwordx4 v164, s[100:101]
	v_mfma_f32_16x16x32_bf16 v[22:25], v[252:255], v[218:221], v[22:25]
	s_add_u32 m0, m0, 0x2000
	v_mfma_f32_16x16x32_bf16 v[18:21], v[152:155], v[218:221], v[18:21]
	global_load_lds_dwordx4 v165, s[100:101]
	v_mfma_f32_16x16x32_bf16 v[14:17], v[244:247], v[224:227], v[14:17]
	s_add_u32 m0, m0, 0x2000
	v_mfma_f32_16x16x32_bf16 v[10:13], v[248:251], v[224:227], v[10:13]
	global_load_lds_dwordx4 v166, s[100:101]
	v_mfma_f32_16x16x32_bf16 v[6:9], v[252:255], v[224:227], v[6:9]
	s_add_u32 m0, m0, 0x2000
	v_mfma_f32_16x16x32_bf16 v[2:5], v[152:155], v[224:227], v[2:5]
	global_load_lds_dwordx4 v167, s[100:101]
	s_branch .Lg2_p2_loop

.Lg2_p4_loop:
	s_nop 0
	ds_read_b128 v[196:199], v148 offset:8192
	ds_read_b128 v[200:203], v148 offset:10240
	ds_read_b128 v[204:207], v148 offset:12288
	ds_read_b128 v[208:211], v148 offset:14336
	s_waitcnt lgkmcnt(4)
	s_nop 0
	v_mfma_f32_16x16x32_bf16 v[126:129], v[212:215], v[180:183], v[126:129]
	v_mfma_f32_16x16x32_bf16 v[122:125], v[218:221], v[180:183], v[122:125]
	v_mfma_f32_16x16x32_bf16 v[118:121], v[224:227], v[180:183], v[118:121]
	v_mfma_f32_16x16x32_bf16 v[114:117], v[228:231], v[180:183], v[114:117]
	v_mfma_f32_16x16x32_bf16 v[110:113], v[212:215], v[184:187], v[110:113]
	v_mfma_f32_16x16x32_bf16 v[106:109], v[218:221], v[184:187], v[106:109]
	v_mfma_f32_16x16x32_bf16 v[102:105], v[224:227], v[184:187], v[102:105]
	v_mfma_f32_16x16x32_bf16 v[98:101], v[228:231], v[184:187], v[98:101]
	v_mfma_f32_16x16x32_bf16 v[94:97], v[212:215], v[188:191], v[94:97]
	v_mfma_f32_16x16x32_bf16 v[90:93], v[218:221], v[188:191], v[90:93]
	v_mfma_f32_16x16x32_bf16 v[86:89], v[224:227], v[188:191], v[86:89]
	v_mfma_f32_16x16x32_bf16 v[82:85], v[228:231], v[188:191], v[82:85]
	v_mfma_f32_16x16x32_bf16 v[78:81], v[212:215], v[192:195], v[78:81]
	v_mfma_f32_16x16x32_bf16 v[74:77], v[218:221], v[192:195], v[74:77]
	v_mfma_f32_16x16x32_bf16 v[70:73], v[224:227], v[192:195], v[70:73]
	v_mfma_f32_16x16x32_bf16 v[66:69], v[228:231], v[192:195], v[66:69]
	ds_read_b128 v[180:183], v216
	ds_read_b128 v[184:187], v216 offset:2048
	ds_read_b128 v[188:191], v216 offset:4096
	ds_read_b128 v[192:195], v216 offset:6144
	ds_read_b128 v[232:235], v217
	ds_read_b128 v[236:239], v217 offset:2048
	ds_read_b128 v[240:243], v217 offset:4096
	ds_read_b128 v[244:247], v217 offset:6144
	s_waitcnt lgkmcnt(8)
	s_nop 0
	v_mfma_f32_16x16x32_bf16 v[62:65], v[212:215], v[196:199], v[62:65]
	v_mfma_f32_16x16x32_bf16 v[58:61], v[218:221], v[196:199], v[58:61]
	v_mfma_f32_16x16x32_bf16 v[54:57], v[224:227], v[196:199], v[54:57]
	v_mfma_f32_16x16x32_bf16 v[50:53], v[228:231], v[196:199], v[50:53]
	v_mfma_f32_16x16x32_bf16 v[46:49], v[212:215], v[200:203], v[46:49]
	v_mfma_f32_16x16x32_bf16 v[42:45], v[218:221], v[200:203], v[42:45]
	v_mfma_f32_16x16x32_bf16 v[38:41], v[224:227], v[200:203], v[38:41]
	v_mfma_f32_16x16x32_bf16 v[34:37], v[228:231], v[200:203], v[34:37]
	v_mfma_f32_16x16x32_bf16 v[30:33], v[212:215], v[204:207], v[30:33]
	v_mfma_f32_16x16x32_bf16 v[26:29], v[218:221], v[204:207], v[26:29]
	v_mfma_f32_16x16x32_bf16 v[22:25], v[224:227], v[204:207], v[22:25]
	v_mfma_f32_16x16x32_bf16 v[18:21], v[228:231], v[204:207], v[18:21]
	v_mfma_f32_16x16x32_bf16 v[14:17], v[212:215], v[208:211], v[14:17]
	v_mfma_f32_16x16x32_bf16 v[10:13], v[218:221], v[208:211], v[10:13]
	v_mfma_f32_16x16x32_bf16 v[6:9], v[224:227], v[208:211], v[6:9]
	v_mfma_f32_16x16x32_bf16 v[2:5], v[228:231], v[208:211], v[2:5]
	ds_read_b128 v[196:199], v216 offset:8192
	ds_read_b128 v[200:203], v216 offset:10240
	ds_read_b128 v[204:207], v216 offset:12288
	ds_read_b128 v[208:211], v216 offset:14336
	s_waitcnt lgkmcnt(4)
	s_nop 0
	v_mfma_f32_16x16x32_bf16 v[126:129], v[232:235], v[180:183], v[126:129]
	v_mfma_f32_16x16x32_bf16 v[122:125], v[236:239], v[180:183], v[122:125]
	v_mfma_f32_16x16x32_bf16 v[118:121], v[240:243], v[180:183], v[118:121]
	v_mfma_f32_16x16x32_bf16 v[114:117], v[244:247], v[180:183], v[114:117]
	v_mfma_f32_16x16x32_bf16 v[110:113], v[232:235], v[184:187], v[110:113]
	v_mfma_f32_16x16x32_bf16 v[106:109], v[236:239], v[184:187], v[106:109]
	v_mfma_f32_16x16x32_bf16 v[102:105], v[240:243], v[184:187], v[102:105]
	v_mfma_f32_16x16x32_bf16 v[98:101], v[244:247], v[184:187], v[98:101]
	v_mfma_f32_16x16x32_bf16 v[94:97], v[232:235], v[188:191], v[94:97]
	v_mfma_f32_16x16x32_bf16 v[90:93], v[236:239], v[188:191], v[90:93]
	v_mfma_f32_16x16x32_bf16 v[86:89], v[240:243], v[188:191], v[86:89]
	v_mfma_f32_16x16x32_bf16 v[82:85], v[244:247], v[188:191], v[82:85]
	v_mfma_f32_16x16x32_bf16 v[78:81], v[232:235], v[192:195], v[78:81]
	v_mfma_f32_16x16x32_bf16 v[74:77], v[236:239], v[192:195], v[74:77]
	v_mfma_f32_16x16x32_bf16 v[70:73], v[240:243], v[192:195], v[70:73]
	v_mfma_f32_16x16x32_bf16 v[66:69], v[244:247], v[192:195], v[66:69]
	s_waitcnt vmcnt(0)
	s_waitcnt lgkmcnt(0)
	s_barrier
	s_add_u32 s8, s8, 0x80
	s_addc_u32 s9, s9, 0
	s_add_u32 s98, s98, 0x80
	s_addc_u32 s99, s99, 0
	s_add_u32 s100, s100, 0x80
	s_addc_u32 s101, s101, 0
	s_cmpk_eq_i32 s8, 0x780
	s_cbranch_scc1 .Lg2_p4_tail
	ds_read_b128 v[180:183], v148 offset:32768
	ds_read_b128 v[184:187], v148 offset:34816
	ds_read_b128 v[188:191], v148 offset:36864
	ds_read_b128 v[192:195], v148 offset:38912
	ds_read_b128 v[212:215], v149 offset:32768
	ds_read_b128 v[218:221], v149 offset:34816
	ds_read_b128 v[224:227], v149 offset:36864
	ds_read_b128 v[228:231], v149 offset:38912
	v_mfma_f32_16x16x32_bf16 v[62:65], v[232:235], v[196:199], v[62:65]
	s_mov_b32 m0, s96
	s_nop 0
	v_mfma_f32_16x16x32_bf16 v[58:61], v[236:239], v[196:199], v[58:61]
	global_load_lds_dwordx4 v140, s[98:99]
	v_mfma_f32_16x16x32_bf16 v[54:57], v[240:243], v[196:199], v[54:57]
	s_add_u32 m0, m0, 0x2000
	v_mfma_f32_16x16x32_bf16 v[50:53], v[244:247], v[196:199], v[50:53]
	global_load_lds_dwordx4 v152, s[98:99]
	v_mfma_f32_16x16x32_bf16 v[46:49], v[232:235], v[200:203], v[46:49]
	s_add_u32 m0, m0, 0x2000
	v_mfma_f32_16x16x32_bf16 v[42:45], v[236:239], v[200:203], v[42:45]
	global_load_lds_dwordx4 v156, s[98:99]
	v_mfma_f32_16x16x32_bf16 v[38:41], v[240:243], v[200:203], v[38:41]
	s_add_u32 m0, m0, 0x2000
	v_mfma_f32_16x16x32_bf16 v[34:37], v[244:247], v[200:203], v[34:37]
	global_load_lds_dwordx4 v160, s[98:99]
	v_mfma_f32_16x16x32_bf16 v[30:33], v[232:235], v[204:207], v[30:33]
	s_add_u32 m0, m0, 0xa000
	v_mfma_f32_16x16x32_bf16 v[26:29], v[236:239], v[204:207], v[26:29]
	global_load_lds_dwordx4 v164, s[100:101]
	v_mfma_f32_16x16x32_bf16 v[22:25], v[240:243], v[204:207], v[22:25]
	s_add_u32 m0, m0, 0x2000
	v_mfma_f32_16x16x32_bf16 v[18:21], v[244:247], v[204:207], v[18:21]
	global_load_lds_dwordx4 v168, s[100:101]
	v_mfma_f32_16x16x32_bf16 v[14:17], v[232:235], v[208:211], v[14:17]
	s_add_u32 m0, m0, 0x2000
	v_mfma_f32_16x16x32_bf16 v[10:13], v[236:239], v[208:211], v[10:13]
	global_load_lds_dwordx4 v172, s[100:101]
	v_mfma_f32_16x16x32_bf16 v[6:9], v[240:243], v[208:211], v[6:9]
	s_add_u32 m0, m0, 0x2000
	v_mfma_f32_16x16x32_bf16 v[2:5], v[244:247], v[208:211], v[2:5]
	global_load_lds_dwordx4 v176, s[100:101]
	ds_read_b128 v[196:199], v148 offset:40960
	ds_read_b128 v[200:203], v148 offset:43008
	ds_read_b128 v[204:207], v148 offset:45056
	ds_read_b128 v[208:211], v148 offset:47104
	s_waitcnt lgkmcnt(4)
	s_nop 0
	v_mfma_f32_16x16x32_bf16 v[126:129], v[212:215], v[180:183], v[126:129]
	v_mfma_f32_16x16x32_bf16 v[122:125], v[218:221], v[180:183], v[122:125]
	v_mfma_f32_16x16x32_bf16 v[118:121], v[224:227], v[180:183], v[118:121]
	v_mfma_f32_16x16x32_bf16 v[114:117], v[228:231], v[180:183], v[114:117]
	v_mfma_f32_16x16x32_bf16 v[110:113], v[212:215], v[184:187], v[110:113]
	v_mfma_f32_16x16x32_bf16 v[106:109], v[218:221], v[184:187], v[106:109]
	v_mfma_f32_16x16x32_bf16 v[102:105], v[224:227], v[184:187], v[102:105]
	v_mfma_f32_16x16x32_bf16 v[98:101], v[228:231], v[184:187], v[98:101]
	v_mfma_f32_16x16x32_bf16 v[94:97], v[212:215], v[188:191], v[94:97]
	v_mfma_f32_16x16x32_bf16 v[90:93], v[218:221], v[188:191], v[90:93]
	v_mfma_f32_16x16x32_bf16 v[86:89], v[224:227], v[188:191], v[86:89]
	v_mfma_f32_16x16x32_bf16 v[82:85], v[228:231], v[188:191], v[82:85]
	v_mfma_f32_16x16x32_bf16 v[78:81], v[212:215], v[192:195], v[78:81]
	v_mfma_f32_16x16x32_bf16 v[74:77], v[218:221], v[192:195], v[74:77]
	v_mfma_f32_16x16x32_bf16 v[70:73], v[224:227], v[192:195], v[70:73]
	v_mfma_f32_16x16x32_bf16 v[66:69], v[228:231], v[192:195], v[66:69]
	ds_read_b128 v[180:183], v216 offset:32768
	ds_read_b128 v[184:187], v216 offset:34816
	ds_read_b128 v[188:191], v216 offset:36864
	ds_read_b128 v[192:195], v216 offset:38912
	ds_read_b128 v[232:235], v217 offset:32768
	ds_read_b128 v[236:239], v217 offset:34816
	ds_read_b128 v[240:243], v217 offset:36864
	ds_read_b128 v[244:247], v217 offset:38912
	s_waitcnt lgkmcnt(8)
	s_nop 0
	v_mfma_f32_16x16x32_bf16 v[62:65], v[212:215], v[196:199], v[62:65]
	v_mfma_f32_16x16x32_bf16 v[58:61], v[218:221], v[196:199], v[58:61]
	v_mfma_f32_16x16x32_bf16 v[54:57], v[224:227], v[196:199], v[54:57]
	v_mfma_f32_16x16x32_bf16 v[50:53], v[228:231], v[196:199], v[50:53]
	v_mfma_f32_16x16x32_bf16 v[46:49], v[212:215], v[200:203], v[46:49]
	v_mfma_f32_16x16x32_bf16 v[42:45], v[218:221], v[200:203], v[42:45]
	v_mfma_f32_16x16x32_bf16 v[38:41], v[224:227], v[200:203], v[38:41]
	v_mfma_f32_16x16x32_bf16 v[34:37], v[228:231], v[200:203], v[34:37]
	v_mfma_f32_16x16x32_bf16 v[30:33], v[212:215], v[204:207], v[30:33]
	v_mfma_f32_16x16x32_bf16 v[26:29], v[218:221], v[204:207], v[26:29]
	v_mfma_f32_16x16x32_bf16 v[22:25], v[224:227], v[204:207], v[22:25]
	v_mfma_f32_16x16x32_bf16 v[18:21], v[228:231], v[204:207], v[18:21]
	v_mfma_f32_16x16x32_bf16 v[14:17], v[212:215], v[208:211], v[14:17]
	v_mfma_f32_16x16x32_bf16 v[10:13], v[218:221], v[208:211], v[10:13]
	v_mfma_f32_16x16x32_bf16 v[6:9], v[224:227], v[208:211], v[6:9]
	v_mfma_f32_16x16x32_bf16 v[2:5], v[228:231], v[208:211], v[2:5]
	ds_read_b128 v[196:199], v216 offset:40960
	ds_read_b128 v[200:203], v216 offset:43008
	ds_read_b128 v[204:207], v216 offset:45056
	ds_read_b128 v[208:211], v216 offset:47104
	s_waitcnt lgkmcnt(4)
	s_nop 0
	v_mfma_f32_16x16x32_bf16 v[126:129], v[232:235], v[180:183], v[126:129]
	v_mfma_f32_16x16x32_bf16 v[122:125], v[236:239], v[180:183], v[122:125]
	v_mfma_f32_16x16x32_bf16 v[118:121], v[240:243], v[180:183], v[118:121]
	v_mfma_f32_16x16x32_bf16 v[114:117], v[244:247], v[180:183], v[114:117]
	v_mfma_f32_16x16x32_bf16 v[110:113], v[232:235], v[184:187], v[110:113]
	v_mfma_f32_16x16x32_bf16 v[106:109], v[236:239], v[184:187], v[106:109]
	v_mfma_f32_16x16x32_bf16 v[102:105], v[240:243], v[184:187], v[102:105]
	v_mfma_f32_16x16x32_bf16 v[98:101], v[244:247], v[184:187], v[98:101]
	v_mfma_f32_16x16x32_bf16 v[94:97], v[232:235], v[188:191], v[94:97]
	v_mfma_f32_16x16x32_bf16 v[90:93], v[236:239], v[188:191], v[90:93]
	v_mfma_f32_16x16x32_bf16 v[86:89], v[240:243], v[188:191], v[86:89]
	v_mfma_f32_16x16x32_bf16 v[82:85], v[244:247], v[188:191], v[82:85]
	v_mfma_f32_16x16x32_bf16 v[78:81], v[232:235], v[192:195], v[78:81]
	v_mfma_f32_16x16x32_bf16 v[74:77], v[236:239], v[192:195], v[74:77]
	v_mfma_f32_16x16x32_bf16 v[70:73], v[240:243], v[192:195], v[70:73]
	v_mfma_f32_16x16x32_bf16 v[66:69], v[244:247], v[192:195], v[66:69]
	s_waitcnt vmcnt(0)
	s_waitcnt lgkmcnt(0)
	s_barrier
	s_add_u32 s8, s8, 0x80
	s_addc_u32 s9, s9, 0
	s_add_u32 s98, s98, 0x80
	s_addc_u32 s99, s99, 0
	s_add_u32 s100, s100, 0x80
	s_addc_u32 s101, s101, 0
	s_cmpk_eq_i32 s8, 0x780
	s_cbranch_scc1 .Lg2_p4_tail
	ds_read_b128 v[180:183], v148
	ds_read_b128 v[184:187], v148 offset:2048
	ds_read_b128 v[188:191], v148 offset:4096
	ds_read_b128 v[192:195], v148 offset:6144
	ds_read_b128 v[212:215], v149
	ds_read_b128 v[218:221], v149 offset:2048
	ds_read_b128 v[224:227], v149 offset:4096
	ds_read_b128 v[228:231], v149 offset:6144
	v_mfma_f32_16x16x32_bf16 v[62:65], v[232:235], v[196:199], v[62:65]
	s_add_u32 m0, s96, 0x8000
	v_mfma_f32_16x16x32_bf16 v[58:61], v[236:239], v[196:199], v[58:61]
	global_load_lds_dwordx4 v140, s[98:99]
	v_mfma_f32_16x16x32_bf16 v[54:57], v[240:243], v[196:199], v[54:57]
	s_add_u32 m0, m0, 0x2000
	v_mfma_f32_16x16x32_bf16 v[50:53], v[244:247], v[196:199], v[50:53]
	global_load_lds_dwordx4 v152, s[98:99]
	v_mfma_f32_16x16x32_bf16 v[46:49], v[232:235], v[200:203], v[46:49]
	s_add_u32 m0, m0, 0x2000
	v_mfma_f32_16x16x32_bf16 v[42:45], v[236:239], v[200:203], v[42:45]
	global_load_lds_dwordx4 v156, s[98:99]
	v_mfma_f32_16x16x32_bf16 v[38:41], v[240:243], v[200:203], v[38:41]
	s_add_u32 m0, m0, 0x2000
	v_mfma_f32_16x16x32_bf16 v[34:37], v[244:247], v[200:203], v[34:37]
	global_load_lds_dwordx4 v160, s[98:99]
	v_mfma_f32_16x16x32_bf16 v[30:33], v[232:235], v[204:207], v[30:33]
	s_add_u32 m0, m0, 0xa000
	v_mfma_f32_16x16x32_bf16 v[26:29], v[236:239], v[204:207], v[26:29]
	global_load_lds_dwordx4 v164, s[100:101]
	v_mfma_f32_16x16x32_bf16 v[22:25], v[240:243], v[204:207], v[22:25]
	s_add_u32 m0, m0, 0x2000
	v_mfma_f32_16x16x32_bf16 v[18:21], v[244:247], v[204:207], v[18:21]
	global_load_lds_dwordx4 v168, s[100:101]
	v_mfma_f32_16x16x32_bf16 v[14:17], v[232:235], v[208:211], v[14:17]
	s_add_u32 m0, m0, 0x2000
	v_mfma_f32_16x16x32_bf16 v[10:13], v[236:239], v[208:211], v[10:13]
	global_load_lds_dwordx4 v172, s[100:101]
	v_mfma_f32_16x16x32_bf16 v[6:9], v[240:243], v[208:211], v[6:9]
	s_add_u32 m0, m0, 0x2000
	v_mfma_f32_16x16x32_bf16 v[2:5], v[244:247], v[208:211], v[2:5]
	global_load_lds_dwordx4 v176, s[100:101]
	s_branch .Lg2_p4_loop

.Lg2_p6_loop:
	ds_read_b128 v[198:201], v146 offset:8192
	ds_read_b128 v[202:205], v146 offset:10240
	ds_read_b128 v[206:209], v146 offset:12288
	ds_read_b128 v[210:213], v146 offset:14336
	s_waitcnt lgkmcnt(4)
	s_nop 0
	v_mfma_f32_16x16x32_bf16 v[126:129], v[218:221], v[182:185], v[126:129]
	v_mfma_f32_16x16x32_bf16 v[122:125], v[224:227], v[182:185], v[122:125]
	v_mfma_f32_16x16x32_bf16 v[118:121], v[228:231], v[182:185], v[118:121]
	v_mfma_f32_16x16x32_bf16 v[114:117], v[232:235], v[182:185], v[114:117]
	v_mfma_f32_16x16x32_bf16 v[110:113], v[218:221], v[186:189], v[110:113]
	v_mfma_f32_16x16x32_bf16 v[106:109], v[224:227], v[186:189], v[106:109]
	v_mfma_f32_16x16x32_bf16 v[102:105], v[228:231], v[186:189], v[102:105]
	v_mfma_f32_16x16x32_bf16 v[98:101], v[232:235], v[186:189], v[98:101]
	v_mfma_f32_16x16x32_bf16 v[94:97], v[218:221], v[190:193], v[94:97]
	v_mfma_f32_16x16x32_bf16 v[90:93], v[224:227], v[190:193], v[90:93]
	v_mfma_f32_16x16x32_bf16 v[86:89], v[228:231], v[190:193], v[86:89]
	v_mfma_f32_16x16x32_bf16 v[82:85], v[232:235], v[190:193], v[82:85]
	v_mfma_f32_16x16x32_bf16 v[78:81], v[218:221], v[194:197], v[78:81]
	v_mfma_f32_16x16x32_bf16 v[74:77], v[224:227], v[194:197], v[74:77]
	v_mfma_f32_16x16x32_bf16 v[70:73], v[228:231], v[194:197], v[70:73]
	v_mfma_f32_16x16x32_bf16 v[66:69], v[232:235], v[194:197], v[66:69]
	ds_read_b128 v[182:185], v216
	ds_read_b128 v[186:189], v216 offset:2048
	ds_read_b128 v[190:193], v216 offset:4096
	ds_read_b128 v[194:197], v216 offset:6144
	ds_read_b128 v[236:239], v217
	ds_read_b128 v[240:243], v217 offset:2048
	ds_read_b128 v[244:247], v217 offset:4096
	ds_read_b128 v[248:251], v217 offset:6144
	s_waitcnt lgkmcnt(8)
	s_nop 0
	v_mfma_f32_16x16x32_bf16 v[62:65], v[218:221], v[198:201], v[62:65]
	v_mfma_f32_16x16x32_bf16 v[58:61], v[224:227], v[198:201], v[58:61]
	v_mfma_f32_16x16x32_bf16 v[54:57], v[228:231], v[198:201], v[54:57]
	v_mfma_f32_16x16x32_bf16 v[50:53], v[232:235], v[198:201], v[50:53]
	v_mfma_f32_16x16x32_bf16 v[46:49], v[218:221], v[202:205], v[46:49]
	v_mfma_f32_16x16x32_bf16 v[42:45], v[224:227], v[202:205], v[42:45]
	v_mfma_f32_16x16x32_bf16 v[38:41], v[228:231], v[202:205], v[38:41]
	v_mfma_f32_16x16x32_bf16 v[34:37], v[232:235], v[202:205], v[34:37]
	v_mfma_f32_16x16x32_bf16 v[30:33], v[218:221], v[206:209], v[30:33]
	v_mfma_f32_16x16x32_bf16 v[26:29], v[224:227], v[206:209], v[26:29]
	v_mfma_f32_16x16x32_bf16 v[22:25], v[228:231], v[206:209], v[22:25]
	v_mfma_f32_16x16x32_bf16 v[18:21], v[232:235], v[206:209], v[18:21]
	v_mfma_f32_16x16x32_bf16 v[14:17], v[218:221], v[210:213], v[14:17]
	v_mfma_f32_16x16x32_bf16 v[10:13], v[224:227], v[210:213], v[10:13]
	v_mfma_f32_16x16x32_bf16 v[6:9], v[228:231], v[210:213], v[6:9]
	v_mfma_f32_16x16x32_bf16 v[2:5], v[232:235], v[210:213], v[2:5]
	ds_read_b128 v[198:201], v216 offset:8192
	ds_read_b128 v[202:205], v216 offset:10240
	ds_read_b128 v[206:209], v216 offset:12288
	ds_read_b128 v[210:213], v216 offset:14336
	s_waitcnt lgkmcnt(4)
	s_nop 0
	v_mfma_f32_16x16x32_bf16 v[126:129], v[236:239], v[182:185], v[126:129]
	v_mfma_f32_16x16x32_bf16 v[122:125], v[240:243], v[182:185], v[122:125]
	v_mfma_f32_16x16x32_bf16 v[118:121], v[244:247], v[182:185], v[118:121]
	v_mfma_f32_16x16x32_bf16 v[114:117], v[248:251], v[182:185], v[114:117]
	v_mfma_f32_16x16x32_bf16 v[110:113], v[236:239], v[186:189], v[110:113]
	v_mfma_f32_16x16x32_bf16 v[106:109], v[240:243], v[186:189], v[106:109]
	v_mfma_f32_16x16x32_bf16 v[102:105], v[244:247], v[186:189], v[102:105]
	v_mfma_f32_16x16x32_bf16 v[98:101], v[248:251], v[186:189], v[98:101]
	v_mfma_f32_16x16x32_bf16 v[94:97], v[236:239], v[190:193], v[94:97]
	v_mfma_f32_16x16x32_bf16 v[90:93], v[240:243], v[190:193], v[90:93]
	v_mfma_f32_16x16x32_bf16 v[86:89], v[244:247], v[190:193], v[86:89]
	v_mfma_f32_16x16x32_bf16 v[82:85], v[248:251], v[190:193], v[82:85]
	v_mfma_f32_16x16x32_bf16 v[78:81], v[236:239], v[194:197], v[78:81]
	v_mfma_f32_16x16x32_bf16 v[74:77], v[240:243], v[194:197], v[74:77]
	v_mfma_f32_16x16x32_bf16 v[70:73], v[244:247], v[194:197], v[70:73]
	v_mfma_f32_16x16x32_bf16 v[66:69], v[248:251], v[194:197], v[66:69]
	s_waitcnt vmcnt(0)
	s_waitcnt lgkmcnt(0)
	s_barrier
	s_add_u32 s0, s0, 0x80
	s_addc_u32 s1, s1, 0
	s_add_u32 s98, s98, 0x80
	s_addc_u32 s99, s99, 0
	s_add_u32 s100, s100, 0x80
	s_addc_u32 s101, s101, 0
	s_cmpk_eq_i32 s0, 0x780
	s_cbranch_scc1 .Lg2_p6_tail
	ds_read_b128 v[182:185], v146 offset:32768
	ds_read_b128 v[186:189], v146 offset:34816
	ds_read_b128 v[190:193], v146 offset:36864
	ds_read_b128 v[194:197], v146 offset:38912
	ds_read_b128 v[218:221], v147 offset:32768
	ds_read_b128 v[224:227], v147 offset:34816
	ds_read_b128 v[228:231], v147 offset:36864
	ds_read_b128 v[232:235], v147 offset:38912
	v_mfma_f32_16x16x32_bf16 v[62:65], v[236:239], v[198:201], v[62:65]
	s_mov_b32 m0, s96
	s_nop 0
	v_mfma_f32_16x16x32_bf16 v[58:61], v[240:243], v[198:201], v[58:61]
	global_load_lds_dwordx4 v150, s[98:99]
	v_mfma_f32_16x16x32_bf16 v[54:57], v[244:247], v[198:201], v[54:57]
	s_add_u32 m0, m0, 0x2000
	v_mfma_f32_16x16x32_bf16 v[50:53], v[248:251], v[198:201], v[50:53]
	global_load_lds_dwordx4 v154, s[98:99]
	v_mfma_f32_16x16x32_bf16 v[46:49], v[236:239], v[202:205], v[46:49]
	s_add_u32 m0, m0, 0x2000
	v_mfma_f32_16x16x32_bf16 v[42:45], v[240:243], v[202:205], v[42:45]
	global_load_lds_dwordx4 v158, s[98:99]
	v_mfma_f32_16x16x32_bf16 v[38:41], v[244:247], v[202:205], v[38:41]
	s_add_u32 m0, m0, 0x2000
	v_mfma_f32_16x16x32_bf16 v[34:37], v[248:251], v[202:205], v[34:37]
	global_load_lds_dwordx4 v162, s[98:99]
	v_mfma_f32_16x16x32_bf16 v[30:33], v[236:239], v[206:209], v[30:33]
	s_add_u32 m0, m0, 0xa000
	v_mfma_f32_16x16x32_bf16 v[26:29], v[240:243], v[206:209], v[26:29]
	global_load_lds_dwordx4 v166, s[100:101]
	v_mfma_f32_16x16x32_bf16 v[22:25], v[244:247], v[206:209], v[22:25]
	s_add_u32 m0, m0, 0x2000
	v_mfma_f32_16x16x32_bf16 v[18:21], v[248:251], v[206:209], v[18:21]
	global_load_lds_dwordx4 v170, s[100:101]
	v_mfma_f32_16x16x32_bf16 v[14:17], v[236:239], v[210:213], v[14:17]
	s_add_u32 m0, m0, 0x2000
	v_mfma_f32_16x16x32_bf16 v[10:13], v[240:243], v[210:213], v[10:13]
	global_load_lds_dwordx4 v174, s[100:101]
	v_mfma_f32_16x16x32_bf16 v[6:9], v[244:247], v[210:213], v[6:9]
	s_add_u32 m0, m0, 0x2000
	v_mfma_f32_16x16x32_bf16 v[2:5], v[248:251], v[210:213], v[2:5]
	global_load_lds_dwordx4 v178, s[100:101]
	ds_read_b128 v[198:201], v146 offset:40960
	ds_read_b128 v[202:205], v146 offset:43008
	ds_read_b128 v[206:209], v146 offset:45056
	ds_read_b128 v[210:213], v146 offset:47104
	s_waitcnt lgkmcnt(4)
	s_nop 0
	v_mfma_f32_16x16x32_bf16 v[126:129], v[218:221], v[182:185], v[126:129]
	v_mfma_f32_16x16x32_bf16 v[122:125], v[224:227], v[182:185], v[122:125]
	v_mfma_f32_16x16x32_bf16 v[118:121], v[228:231], v[182:185], v[118:121]
	v_mfma_f32_16x16x32_bf16 v[114:117], v[232:235], v[182:185], v[114:117]
	v_mfma_f32_16x16x32_bf16 v[110:113], v[218:221], v[186:189], v[110:113]
	v_mfma_f32_16x16x32_bf16 v[106:109], v[224:227], v[186:189], v[106:109]
	v_mfma_f32_16x16x32_bf16 v[102:105], v[228:231], v[186:189], v[102:105]
	v_mfma_f32_16x16x32_bf16 v[98:101], v[232:235], v[186:189], v[98:101]
	v_mfma_f32_16x16x32_bf16 v[94:97], v[218:221], v[190:193], v[94:97]
	v_mfma_f32_16x16x32_bf16 v[90:93], v[224:227], v[190:193], v[90:93]
	v_mfma_f32_16x16x32_bf16 v[86:89], v[228:231], v[190:193], v[86:89]
	v_mfma_f32_16x16x32_bf16 v[82:85], v[232:235], v[190:193], v[82:85]
	v_mfma_f32_16x16x32_bf16 v[78:81], v[218:221], v[194:197], v[78:81]
	v_mfma_f32_16x16x32_bf16 v[74:77], v[224:227], v[194:197], v[74:77]
	v_mfma_f32_16x16x32_bf16 v[70:73], v[228:231], v[194:197], v[70:73]
	v_mfma_f32_16x16x32_bf16 v[66:69], v[232:235], v[194:197], v[66:69]
	ds_read_b128 v[182:185], v216 offset:32768
	ds_read_b128 v[186:189], v216 offset:34816
	ds_read_b128 v[190:193], v216 offset:36864
	ds_read_b128 v[194:197], v216 offset:38912
	ds_read_b128 v[236:239], v217 offset:32768
	ds_read_b128 v[240:243], v217 offset:34816
	ds_read_b128 v[244:247], v217 offset:36864
	ds_read_b128 v[248:251], v217 offset:38912
	s_waitcnt lgkmcnt(8)
	s_nop 0
	v_mfma_f32_16x16x32_bf16 v[62:65], v[218:221], v[198:201], v[62:65]
	v_mfma_f32_16x16x32_bf16 v[58:61], v[224:227], v[198:201], v[58:61]
	v_mfma_f32_16x16x32_bf16 v[54:57], v[228:231], v[198:201], v[54:57]
	v_mfma_f32_16x16x32_bf16 v[50:53], v[232:235], v[198:201], v[50:53]
	v_mfma_f32_16x16x32_bf16 v[46:49], v[218:221], v[202:205], v[46:49]
	v_mfma_f32_16x16x32_bf16 v[42:45], v[224:227], v[202:205], v[42:45]
	v_mfma_f32_16x16x32_bf16 v[38:41], v[228:231], v[202:205], v[38:41]
	v_mfma_f32_16x16x32_bf16 v[34:37], v[232:235], v[202:205], v[34:37]
	v_mfma_f32_16x16x32_bf16 v[30:33], v[218:221], v[206:209], v[30:33]
	v_mfma_f32_16x16x32_bf16 v[26:29], v[224:227], v[206:209], v[26:29]
	v_mfma_f32_16x16x32_bf16 v[22:25], v[228:231], v[206:209], v[22:25]
	v_mfma_f32_16x16x32_bf16 v[18:21], v[232:235], v[206:209], v[18:21]
	v_mfma_f32_16x16x32_bf16 v[14:17], v[218:221], v[210:213], v[14:17]
	v_mfma_f32_16x16x32_bf16 v[10:13], v[224:227], v[210:213], v[10:13]
	v_mfma_f32_16x16x32_bf16 v[6:9], v[228:231], v[210:213], v[6:9]
	v_mfma_f32_16x16x32_bf16 v[2:5], v[232:235], v[210:213], v[2:5]
	ds_read_b128 v[198:201], v216 offset:40960
	ds_read_b128 v[202:205], v216 offset:43008
	ds_read_b128 v[206:209], v216 offset:45056
	ds_read_b128 v[210:213], v216 offset:47104
	s_waitcnt lgkmcnt(4)
	s_nop 0
	v_mfma_f32_16x16x32_bf16 v[126:129], v[236:239], v[182:185], v[126:129]
	v_mfma_f32_16x16x32_bf16 v[122:125], v[240:243], v[182:185], v[122:125]
	v_mfma_f32_16x16x32_bf16 v[118:121], v[244:247], v[182:185], v[118:121]
	v_mfma_f32_16x16x32_bf16 v[114:117], v[248:251], v[182:185], v[114:117]
	v_mfma_f32_16x16x32_bf16 v[110:113], v[236:239], v[186:189], v[110:113]
	v_mfma_f32_16x16x32_bf16 v[106:109], v[240:243], v[186:189], v[106:109]
	v_mfma_f32_16x16x32_bf16 v[102:105], v[244:247], v[186:189], v[102:105]
	v_mfma_f32_16x16x32_bf16 v[98:101], v[248:251], v[186:189], v[98:101]
	v_mfma_f32_16x16x32_bf16 v[94:97], v[236:239], v[190:193], v[94:97]
	v_mfma_f32_16x16x32_bf16 v[90:93], v[240:243], v[190:193], v[90:93]
	v_mfma_f32_16x16x32_bf16 v[86:89], v[244:247], v[190:193], v[86:89]
	v_mfma_f32_16x16x32_bf16 v[82:85], v[248:251], v[190:193], v[82:85]
	v_mfma_f32_16x16x32_bf16 v[78:81], v[236:239], v[194:197], v[78:81]
	v_mfma_f32_16x16x32_bf16 v[74:77], v[240:243], v[194:197], v[74:77]
	v_mfma_f32_16x16x32_bf16 v[70:73], v[244:247], v[194:197], v[70:73]
	v_mfma_f32_16x16x32_bf16 v[66:69], v[248:251], v[194:197], v[66:69]
	s_waitcnt vmcnt(0)
	s_waitcnt lgkmcnt(0)
	s_barrier
	s_add_u32 s0, s0, 0x80
	s_addc_u32 s1, s1, 0
	s_add_u32 s98, s98, 0x80
	s_addc_u32 s99, s99, 0
	s_add_u32 s100, s100, 0x80
	s_addc_u32 s101, s101, 0
	s_cmpk_eq_i32 s0, 0x780
	s_cbranch_scc1 .Lg2_p6_tail
	ds_read_b128 v[182:185], v146
	ds_read_b128 v[186:189], v146 offset:2048
	ds_read_b128 v[190:193], v146 offset:4096
	ds_read_b128 v[194:197], v146 offset:6144
	ds_read_b128 v[218:221], v147
	ds_read_b128 v[224:227], v147 offset:2048
	ds_read_b128 v[228:231], v147 offset:4096
	ds_read_b128 v[232:235], v147 offset:6144
	v_mfma_f32_16x16x32_bf16 v[62:65], v[236:239], v[198:201], v[62:65]
	s_add_u32 m0, s96, 0x8000
	v_mfma_f32_16x16x32_bf16 v[58:61], v[240:243], v[198:201], v[58:61]
	global_load_lds_dwordx4 v150, s[98:99]
	v_mfma_f32_16x16x32_bf16 v[54:57], v[244:247], v[198:201], v[54:57]
	s_add_u32 m0, m0, 0x2000
	v_mfma_f32_16x16x32_bf16 v[50:53], v[248:251], v[198:201], v[50:53]
	global_load_lds_dwordx4 v154, s[98:99]
	v_mfma_f32_16x16x32_bf16 v[46:49], v[236:239], v[202:205], v[46:49]
	s_add_u32 m0, m0, 0x2000
	v_mfma_f32_16x16x32_bf16 v[42:45], v[240:243], v[202:205], v[42:45]
	global_load_lds_dwordx4 v158, s[98:99]
	v_mfma_f32_16x16x32_bf16 v[38:41], v[244:247], v[202:205], v[38:41]
	s_add_u32 m0, m0, 0x2000
	v_mfma_f32_16x16x32_bf16 v[34:37], v[248:251], v[202:205], v[34:37]
	global_load_lds_dwordx4 v162, s[98:99]
	v_mfma_f32_16x16x32_bf16 v[30:33], v[236:239], v[206:209], v[30:33]
	s_add_u32 m0, m0, 0xa000
	v_mfma_f32_16x16x32_bf16 v[26:29], v[240:243], v[206:209], v[26:29]
	global_load_lds_dwordx4 v166, s[100:101]
	v_mfma_f32_16x16x32_bf16 v[22:25], v[244:247], v[206:209], v[22:25]
	s_add_u32 m0, m0, 0x2000
	v_mfma_f32_16x16x32_bf16 v[18:21], v[248:251], v[206:209], v[18:21]
	global_load_lds_dwordx4 v170, s[100:101]
	v_mfma_f32_16x16x32_bf16 v[14:17], v[236:239], v[210:213], v[14:17]
	s_add_u32 m0, m0, 0x2000
	v_mfma_f32_16x16x32_bf16 v[10:13], v[240:243], v[210:213], v[10:13]
	global_load_lds_dwordx4 v174, s[100:101]
	v_mfma_f32_16x16x32_bf16 v[6:9], v[244:247], v[210:213], v[6:9]
	s_add_u32 m0, m0, 0x2000
	v_mfma_f32_16x16x32_bf16 v[2:5], v[248:251], v[210:213], v[2:5]
	global_load_lds_dwordx4 v178, s[100:101]
	s_branch .Lg2_p6_loop

.Lg2_p7_loop:
	ds_read_b128 v[196:199], v148 offset:8192
	ds_read_b128 v[200:203], v148 offset:10240
	ds_read_b128 v[204:207], v148 offset:12288
	ds_read_b128 v[208:211], v148 offset:14336
	s_waitcnt lgkmcnt(4)
	s_nop 0
	v_mfma_f32_16x16x32_bf16 v[126:129], v[212:215], v[180:183], v[126:129]
	v_mfma_f32_16x16x32_bf16 v[122:125], v[218:221], v[180:183], v[122:125]
	v_mfma_f32_16x16x32_bf16 v[118:121], v[224:227], v[180:183], v[118:121]
	v_mfma_f32_16x16x32_bf16 v[114:117], v[228:231], v[180:183], v[114:117]
	v_mfma_f32_16x16x32_bf16 v[110:113], v[212:215], v[184:187], v[110:113]
	v_mfma_f32_16x16x32_bf16 v[106:109], v[218:221], v[184:187], v[106:109]
	v_mfma_f32_16x16x32_bf16 v[102:105], v[224:227], v[184:187], v[102:105]
	v_mfma_f32_16x16x32_bf16 v[98:101], v[228:231], v[184:187], v[98:101]
	v_mfma_f32_16x16x32_bf16 v[94:97], v[212:215], v[188:191], v[94:97]
	v_mfma_f32_16x16x32_bf16 v[90:93], v[218:221], v[188:191], v[90:93]
	v_mfma_f32_16x16x32_bf16 v[86:89], v[224:227], v[188:191], v[86:89]
	v_mfma_f32_16x16x32_bf16 v[82:85], v[228:231], v[188:191], v[82:85]
	v_mfma_f32_16x16x32_bf16 v[78:81], v[212:215], v[192:195], v[78:81]
	v_mfma_f32_16x16x32_bf16 v[74:77], v[218:221], v[192:195], v[74:77]
	v_mfma_f32_16x16x32_bf16 v[70:73], v[224:227], v[192:195], v[70:73]
	v_mfma_f32_16x16x32_bf16 v[66:69], v[228:231], v[192:195], v[66:69]
	ds_read_b128 v[180:183], v216
	ds_read_b128 v[184:187], v216 offset:2048
	ds_read_b128 v[188:191], v216 offset:4096
	ds_read_b128 v[192:195], v216 offset:6144
	ds_read_b128 v[232:235], v217
	ds_read_b128 v[236:239], v217 offset:2048
	ds_read_b128 v[240:243], v217 offset:4096
	ds_read_b128 v[244:247], v217 offset:6144
	s_waitcnt lgkmcnt(8)
	s_nop 0
	v_mfma_f32_16x16x32_bf16 v[62:65], v[212:215], v[196:199], v[62:65]
	v_mfma_f32_16x16x32_bf16 v[58:61], v[218:221], v[196:199], v[58:61]
	v_mfma_f32_16x16x32_bf16 v[54:57], v[224:227], v[196:199], v[54:57]
	v_mfma_f32_16x16x32_bf16 v[50:53], v[228:231], v[196:199], v[50:53]
	v_mfma_f32_16x16x32_bf16 v[46:49], v[212:215], v[200:203], v[46:49]
	v_mfma_f32_16x16x32_bf16 v[42:45], v[218:221], v[200:203], v[42:45]
	v_mfma_f32_16x16x32_bf16 v[38:41], v[224:227], v[200:203], v[38:41]
	v_mfma_f32_16x16x32_bf16 v[34:37], v[228:231], v[200:203], v[34:37]
	v_mfma_f32_16x16x32_bf16 v[30:33], v[212:215], v[204:207], v[30:33]
	v_mfma_f32_16x16x32_bf16 v[26:29], v[218:221], v[204:207], v[26:29]
	v_mfma_f32_16x16x32_bf16 v[22:25], v[224:227], v[204:207], v[22:25]
	v_mfma_f32_16x16x32_bf16 v[18:21], v[228:231], v[204:207], v[18:21]
	v_mfma_f32_16x16x32_bf16 v[14:17], v[212:215], v[208:211], v[14:17]
	v_mfma_f32_16x16x32_bf16 v[10:13], v[218:221], v[208:211], v[10:13]
	v_mfma_f32_16x16x32_bf16 v[6:9], v[224:227], v[208:211], v[6:9]
	v_mfma_f32_16x16x32_bf16 v[2:5], v[228:231], v[208:211], v[2:5]
	ds_read_b128 v[196:199], v216 offset:8192
	ds_read_b128 v[200:203], v216 offset:10240
	ds_read_b128 v[204:207], v216 offset:12288
	ds_read_b128 v[208:211], v216 offset:14336
	s_waitcnt lgkmcnt(4)
	s_nop 0
	v_mfma_f32_16x16x32_bf16 v[126:129], v[232:235], v[180:183], v[126:129]
	v_mfma_f32_16x16x32_bf16 v[122:125], v[236:239], v[180:183], v[122:125]
	v_mfma_f32_16x16x32_bf16 v[118:121], v[240:243], v[180:183], v[118:121]
	v_mfma_f32_16x16x32_bf16 v[114:117], v[244:247], v[180:183], v[114:117]
	v_mfma_f32_16x16x32_bf16 v[110:113], v[232:235], v[184:187], v[110:113]
	v_mfma_f32_16x16x32_bf16 v[106:109], v[236:239], v[184:187], v[106:109]
	v_mfma_f32_16x16x32_bf16 v[102:105], v[240:243], v[184:187], v[102:105]
	v_mfma_f32_16x16x32_bf16 v[98:101], v[244:247], v[184:187], v[98:101]
	v_mfma_f32_16x16x32_bf16 v[94:97], v[232:235], v[188:191], v[94:97]
	v_mfma_f32_16x16x32_bf16 v[90:93], v[236:239], v[188:191], v[90:93]
	v_mfma_f32_16x16x32_bf16 v[86:89], v[240:243], v[188:191], v[86:89]
	v_mfma_f32_16x16x32_bf16 v[82:85], v[244:247], v[188:191], v[82:85]
	v_mfma_f32_16x16x32_bf16 v[78:81], v[232:235], v[192:195], v[78:81]
	v_mfma_f32_16x16x32_bf16 v[74:77], v[236:239], v[192:195], v[74:77]
	v_mfma_f32_16x16x32_bf16 v[70:73], v[240:243], v[192:195], v[70:73]
	v_mfma_f32_16x16x32_bf16 v[66:69], v[244:247], v[192:195], v[66:69]
	s_waitcnt vmcnt(0)
	s_waitcnt lgkmcnt(0)
	s_barrier
	s_add_u32 s8, s8, 0x80
	s_addc_u32 s9, s9, 0
	s_add_u32 s98, s98, 0x80
	s_addc_u32 s99, s99, 0
	s_add_u32 s100, s100, 0x80
	s_addc_u32 s101, s101, 0
	s_cmpk_eq_i32 s8, 0x1580
	s_cbranch_scc1 .Lg2_p7_tail
	ds_read_b128 v[180:183], v148 offset:32768
	ds_read_b128 v[184:187], v148 offset:34816
	ds_read_b128 v[188:191], v148 offset:36864
	ds_read_b128 v[192:195], v148 offset:38912
	ds_read_b128 v[212:215], v149 offset:32768
	ds_read_b128 v[218:221], v149 offset:34816
	ds_read_b128 v[224:227], v149 offset:36864
	ds_read_b128 v[228:231], v149 offset:38912
	v_mfma_f32_16x16x32_bf16 v[62:65], v[232:235], v[196:199], v[62:65]
	s_mov_b32 m0, s96
	s_nop 0
	v_mfma_f32_16x16x32_bf16 v[58:61], v[236:239], v[196:199], v[58:61]
	global_load_lds_dwordx4 v140, s[98:99]
	v_mfma_f32_16x16x32_bf16 v[54:57], v[240:243], v[196:199], v[54:57]
	s_add_u32 m0, m0, 0x2000
	v_mfma_f32_16x16x32_bf16 v[50:53], v[244:247], v[196:199], v[50:53]
	global_load_lds_dwordx4 v152, s[98:99]
	v_mfma_f32_16x16x32_bf16 v[46:49], v[232:235], v[200:203], v[46:49]
	s_add_u32 m0, m0, 0x2000
	v_mfma_f32_16x16x32_bf16 v[42:45], v[236:239], v[200:203], v[42:45]
	global_load_lds_dwordx4 v156, s[98:99]
	v_mfma_f32_16x16x32_bf16 v[38:41], v[240:243], v[200:203], v[38:41]
	s_add_u32 m0, m0, 0x2000
	v_mfma_f32_16x16x32_bf16 v[34:37], v[244:247], v[200:203], v[34:37]
	global_load_lds_dwordx4 v160, s[98:99]
	v_mfma_f32_16x16x32_bf16 v[30:33], v[232:235], v[204:207], v[30:33]
	s_add_u32 m0, m0, 0xa000
	v_mfma_f32_16x16x32_bf16 v[26:29], v[236:239], v[204:207], v[26:29]
	global_load_lds_dwordx4 v164, s[100:101]
	v_mfma_f32_16x16x32_bf16 v[22:25], v[240:243], v[204:207], v[22:25]
	s_add_u32 m0, m0, 0x2000
	v_mfma_f32_16x16x32_bf16 v[18:21], v[244:247], v[204:207], v[18:21]
	global_load_lds_dwordx4 v168, s[100:101]
	v_mfma_f32_16x16x32_bf16 v[14:17], v[232:235], v[208:211], v[14:17]
	s_add_u32 m0, m0, 0x2000
	v_mfma_f32_16x16x32_bf16 v[10:13], v[236:239], v[208:211], v[10:13]
	global_load_lds_dwordx4 v172, s[100:101]
	v_mfma_f32_16x16x32_bf16 v[6:9], v[240:243], v[208:211], v[6:9]
	s_add_u32 m0, m0, 0x2000
	v_mfma_f32_16x16x32_bf16 v[2:5], v[244:247], v[208:211], v[2:5]
	global_load_lds_dwordx4 v176, s[100:101]
	ds_read_b128 v[196:199], v148 offset:40960
	ds_read_b128 v[200:203], v148 offset:43008
	ds_read_b128 v[204:207], v148 offset:45056
	ds_read_b128 v[208:211], v148 offset:47104
	s_waitcnt lgkmcnt(4)
	s_nop 0
	v_mfma_f32_16x16x32_bf16 v[126:129], v[212:215], v[180:183], v[126:129]
	v_mfma_f32_16x16x32_bf16 v[122:125], v[218:221], v[180:183], v[122:125]
	v_mfma_f32_16x16x32_bf16 v[118:121], v[224:227], v[180:183], v[118:121]
	v_mfma_f32_16x16x32_bf16 v[114:117], v[228:231], v[180:183], v[114:117]
	v_mfma_f32_16x16x32_bf16 v[110:113], v[212:215], v[184:187], v[110:113]
	v_mfma_f32_16x16x32_bf16 v[106:109], v[218:221], v[184:187], v[106:109]
	v_mfma_f32_16x16x32_bf16 v[102:105], v[224:227], v[184:187], v[102:105]
	v_mfma_f32_16x16x32_bf16 v[98:101], v[228:231], v[184:187], v[98:101]
	v_mfma_f32_16x16x32_bf16 v[94:97], v[212:215], v[188:191], v[94:97]
	v_mfma_f32_16x16x32_bf16 v[90:93], v[218:221], v[188:191], v[90:93]
	v_mfma_f32_16x16x32_bf16 v[86:89], v[224:227], v[188:191], v[86:89]
	v_mfma_f32_16x16x32_bf16 v[82:85], v[228:231], v[188:191], v[82:85]
	v_mfma_f32_16x16x32_bf16 v[78:81], v[212:215], v[192:195], v[78:81]
	v_mfma_f32_16x16x32_bf16 v[74:77], v[218:221], v[192:195], v[74:77]
	v_mfma_f32_16x16x32_bf16 v[70:73], v[224:227], v[192:195], v[70:73]
	v_mfma_f32_16x16x32_bf16 v[66:69], v[228:231], v[192:195], v[66:69]
	ds_read_b128 v[180:183], v216 offset:32768
	ds_read_b128 v[184:187], v216 offset:34816
	ds_read_b128 v[188:191], v216 offset:36864
	ds_read_b128 v[192:195], v216 offset:38912
	ds_read_b128 v[232:235], v217 offset:32768
	ds_read_b128 v[236:239], v217 offset:34816
	ds_read_b128 v[240:243], v217 offset:36864
	ds_read_b128 v[244:247], v217 offset:38912
	s_waitcnt lgkmcnt(8)
	s_nop 0
	v_mfma_f32_16x16x32_bf16 v[62:65], v[212:215], v[196:199], v[62:65]
	v_mfma_f32_16x16x32_bf16 v[58:61], v[218:221], v[196:199], v[58:61]
	v_mfma_f32_16x16x32_bf16 v[54:57], v[224:227], v[196:199], v[54:57]
	v_mfma_f32_16x16x32_bf16 v[50:53], v[228:231], v[196:199], v[50:53]
	v_mfma_f32_16x16x32_bf16 v[46:49], v[212:215], v[200:203], v[46:49]
	v_mfma_f32_16x16x32_bf16 v[42:45], v[218:221], v[200:203], v[42:45]
	v_mfma_f32_16x16x32_bf16 v[38:41], v[224:227], v[200:203], v[38:41]
	v_mfma_f32_16x16x32_bf16 v[34:37], v[228:231], v[200:203], v[34:37]
	v_mfma_f32_16x16x32_bf16 v[30:33], v[212:215], v[204:207], v[30:33]
	v_mfma_f32_16x16x32_bf16 v[26:29], v[218:221], v[204:207], v[26:29]
	v_mfma_f32_16x16x32_bf16 v[22:25], v[224:227], v[204:207], v[22:25]
	v_mfma_f32_16x16x32_bf16 v[18:21], v[228:231], v[204:207], v[18:21]
	v_mfma_f32_16x16x32_bf16 v[14:17], v[212:215], v[208:211], v[14:17]
	v_mfma_f32_16x16x32_bf16 v[10:13], v[218:221], v[208:211], v[10:13]
	v_mfma_f32_16x16x32_bf16 v[6:9], v[224:227], v[208:211], v[6:9]
	v_mfma_f32_16x16x32_bf16 v[2:5], v[228:231], v[208:211], v[2:5]
	ds_read_b128 v[196:199], v216 offset:40960
	ds_read_b128 v[200:203], v216 offset:43008
	ds_read_b128 v[204:207], v216 offset:45056
	ds_read_b128 v[208:211], v216 offset:47104
	s_waitcnt lgkmcnt(4)
	s_nop 0
	v_mfma_f32_16x16x32_bf16 v[126:129], v[232:235], v[180:183], v[126:129]
	v_mfma_f32_16x16x32_bf16 v[122:125], v[236:239], v[180:183], v[122:125]
	v_mfma_f32_16x16x32_bf16 v[118:121], v[240:243], v[180:183], v[118:121]
	v_mfma_f32_16x16x32_bf16 v[114:117], v[244:247], v[180:183], v[114:117]
	v_mfma_f32_16x16x32_bf16 v[110:113], v[232:235], v[184:187], v[110:113]
	v_mfma_f32_16x16x32_bf16 v[106:109], v[236:239], v[184:187], v[106:109]
	v_mfma_f32_16x16x32_bf16 v[102:105], v[240:243], v[184:187], v[102:105]
	v_mfma_f32_16x16x32_bf16 v[98:101], v[244:247], v[184:187], v[98:101]
	v_mfma_f32_16x16x32_bf16 v[94:97], v[232:235], v[188:191], v[94:97]
	v_mfma_f32_16x16x32_bf16 v[90:93], v[236:239], v[188:191], v[90:93]
	v_mfma_f32_16x16x32_bf16 v[86:89], v[240:243], v[188:191], v[86:89]
	v_mfma_f32_16x16x32_bf16 v[82:85], v[244:247], v[188:191], v[82:85]
	v_mfma_f32_16x16x32_bf16 v[78:81], v[232:235], v[192:195], v[78:81]
	v_mfma_f32_16x16x32_bf16 v[74:77], v[236:239], v[192:195], v[74:77]
	v_mfma_f32_16x16x32_bf16 v[70:73], v[240:243], v[192:195], v[70:73]
	v_mfma_f32_16x16x32_bf16 v[66:69], v[244:247], v[192:195], v[66:69]
	s_waitcnt vmcnt(0)
	s_waitcnt lgkmcnt(0)
	s_barrier
	s_add_u32 s8, s8, 0x80
	s_addc_u32 s9, s9, 0
	s_add_u32 s98, s98, 0x80
	s_addc_u32 s99, s99, 0
	s_add_u32 s100, s100, 0x80
	s_addc_u32 s101, s101, 0
	s_cmpk_eq_i32 s8, 0x1580
	s_cbranch_scc1 .Lg2_p7_tail
	ds_read_b128 v[180:183], v148
	ds_read_b128 v[184:187], v148 offset:2048
	ds_read_b128 v[188:191], v148 offset:4096
	ds_read_b128 v[192:195], v148 offset:6144
	ds_read_b128 v[212:215], v149
	ds_read_b128 v[218:221], v149 offset:2048
	ds_read_b128 v[224:227], v149 offset:4096
	ds_read_b128 v[228:231], v149 offset:6144
	v_mfma_f32_16x16x32_bf16 v[62:65], v[232:235], v[196:199], v[62:65]
	s_add_u32 m0, s96, 0x8000
	v_mfma_f32_16x16x32_bf16 v[58:61], v[236:239], v[196:199], v[58:61]
	global_load_lds_dwordx4 v140, s[98:99]
	v_mfma_f32_16x16x32_bf16 v[54:57], v[240:243], v[196:199], v[54:57]
	s_add_u32 m0, m0, 0x2000
	v_mfma_f32_16x16x32_bf16 v[50:53], v[244:247], v[196:199], v[50:53]
	global_load_lds_dwordx4 v152, s[98:99]
	v_mfma_f32_16x16x32_bf16 v[46:49], v[232:235], v[200:203], v[46:49]
	s_add_u32 m0, m0, 0x2000
	v_mfma_f32_16x16x32_bf16 v[42:45], v[236:239], v[200:203], v[42:45]
	global_load_lds_dwordx4 v156, s[98:99]
	v_mfma_f32_16x16x32_bf16 v[38:41], v[240:243], v[200:203], v[38:41]
	s_add_u32 m0, m0, 0x2000
	v_mfma_f32_16x16x32_bf16 v[34:37], v[244:247], v[200:203], v[34:37]
	global_load_lds_dwordx4 v160, s[98:99]
	v_mfma_f32_16x16x32_bf16 v[30:33], v[232:235], v[204:207], v[30:33]
	s_add_u32 m0, m0, 0xa000
	v_mfma_f32_16x16x32_bf16 v[26:29], v[236:239], v[204:207], v[26:29]
	global_load_lds_dwordx4 v164, s[100:101]
	v_mfma_f32_16x16x32_bf16 v[22:25], v[240:243], v[204:207], v[22:25]
	s_add_u32 m0, m0, 0x2000
	v_mfma_f32_16x16x32_bf16 v[18:21], v[244:247], v[204:207], v[18:21]
	global_load_lds_dwordx4 v168, s[100:101]
	v_mfma_f32_16x16x32_bf16 v[14:17], v[232:235], v[208:211], v[14:17]
	s_add_u32 m0, m0, 0x2000
	v_mfma_f32_16x16x32_bf16 v[10:13], v[236:239], v[208:211], v[10:13]
	global_load_lds_dwordx4 v172, s[100:101]
	v_mfma_f32_16x16x32_bf16 v[6:9], v[240:243], v[208:211], v[6:9]
	s_add_u32 m0, m0, 0x2000
	v_mfma_f32_16x16x32_bf16 v[2:5], v[244:247], v[208:211], v[2:5]
	global_load_lds_dwordx4 v176, s[100:101]
	s_branch .Lg2_p7_loop

.Lg2_p12_loop:
	ds_read_b128 v[196:199], v148 offset:8192
	ds_read_b128 v[200:203], v148 offset:10240
	ds_read_b128 v[204:207], v148 offset:12288
	ds_read_b128 v[208:211], v148 offset:14336
	s_waitcnt lgkmcnt(4)
	s_nop 0
	v_mfma_f32_16x16x32_bf16 v[126:129], v[212:215], v[180:183], v[126:129]
	v_mfma_f32_16x16x32_bf16 v[122:125], v[218:221], v[180:183], v[122:125]
	v_mfma_f32_16x16x32_bf16 v[118:121], v[224:227], v[180:183], v[118:121]
	v_mfma_f32_16x16x32_bf16 v[114:117], v[228:231], v[180:183], v[114:117]
	v_mfma_f32_16x16x32_bf16 v[110:113], v[212:215], v[184:187], v[110:113]
	v_mfma_f32_16x16x32_bf16 v[106:109], v[218:221], v[184:187], v[106:109]
	v_mfma_f32_16x16x32_bf16 v[102:105], v[224:227], v[184:187], v[102:105]
	v_mfma_f32_16x16x32_bf16 v[98:101], v[228:231], v[184:187], v[98:101]
	v_mfma_f32_16x16x32_bf16 v[94:97], v[212:215], v[188:191], v[94:97]
	v_mfma_f32_16x16x32_bf16 v[90:93], v[218:221], v[188:191], v[90:93]
	v_mfma_f32_16x16x32_bf16 v[86:89], v[224:227], v[188:191], v[86:89]
	v_mfma_f32_16x16x32_bf16 v[82:85], v[228:231], v[188:191], v[82:85]
	v_mfma_f32_16x16x32_bf16 v[78:81], v[212:215], v[192:195], v[78:81]
	v_mfma_f32_16x16x32_bf16 v[74:77], v[218:221], v[192:195], v[74:77]
	v_mfma_f32_16x16x32_bf16 v[70:73], v[224:227], v[192:195], v[70:73]
	v_mfma_f32_16x16x32_bf16 v[66:69], v[228:231], v[192:195], v[66:69]
	ds_read_b128 v[180:183], v216
	ds_read_b128 v[184:187], v216 offset:2048
	ds_read_b128 v[188:191], v216 offset:4096
	ds_read_b128 v[192:195], v216 offset:6144
	ds_read_b128 v[232:235], v217
	ds_read_b128 v[236:239], v217 offset:2048
	ds_read_b128 v[240:243], v217 offset:4096
	ds_read_b128 v[244:247], v217 offset:6144
	s_waitcnt lgkmcnt(8)
	s_nop 0
	v_mfma_f32_16x16x32_bf16 v[62:65], v[212:215], v[196:199], v[62:65]
	v_mfma_f32_16x16x32_bf16 v[58:61], v[218:221], v[196:199], v[58:61]
	v_mfma_f32_16x16x32_bf16 v[54:57], v[224:227], v[196:199], v[54:57]
	v_mfma_f32_16x16x32_bf16 v[50:53], v[228:231], v[196:199], v[50:53]
	v_mfma_f32_16x16x32_bf16 v[46:49], v[212:215], v[200:203], v[46:49]
	v_mfma_f32_16x16x32_bf16 v[42:45], v[218:221], v[200:203], v[42:45]
	v_mfma_f32_16x16x32_bf16 v[38:41], v[224:227], v[200:203], v[38:41]
	v_mfma_f32_16x16x32_bf16 v[34:37], v[228:231], v[200:203], v[34:37]
	v_mfma_f32_16x16x32_bf16 v[30:33], v[212:215], v[204:207], v[30:33]
	v_mfma_f32_16x16x32_bf16 v[26:29], v[218:221], v[204:207], v[26:29]
	v_mfma_f32_16x16x32_bf16 v[22:25], v[224:227], v[204:207], v[22:25]
	v_mfma_f32_16x16x32_bf16 v[18:21], v[228:231], v[204:207], v[18:21]
	v_mfma_f32_16x16x32_bf16 v[14:17], v[212:215], v[208:211], v[14:17]
	v_mfma_f32_16x16x32_bf16 v[10:13], v[218:221], v[208:211], v[10:13]
	v_mfma_f32_16x16x32_bf16 v[6:9], v[224:227], v[208:211], v[6:9]
	v_mfma_f32_16x16x32_bf16 v[2:5], v[228:231], v[208:211], v[2:5]
	ds_read_b128 v[196:199], v216 offset:8192
	ds_read_b128 v[200:203], v216 offset:10240
	ds_read_b128 v[204:207], v216 offset:12288
	ds_read_b128 v[208:211], v216 offset:14336
	s_waitcnt lgkmcnt(4)
	s_nop 0
	v_mfma_f32_16x16x32_bf16 v[126:129], v[232:235], v[180:183], v[126:129]
	v_mfma_f32_16x16x32_bf16 v[122:125], v[236:239], v[180:183], v[122:125]
	v_mfma_f32_16x16x32_bf16 v[118:121], v[240:243], v[180:183], v[118:121]
	v_mfma_f32_16x16x32_bf16 v[114:117], v[244:247], v[180:183], v[114:117]
	v_mfma_f32_16x16x32_bf16 v[110:113], v[232:235], v[184:187], v[110:113]
	v_mfma_f32_16x16x32_bf16 v[106:109], v[236:239], v[184:187], v[106:109]
	v_mfma_f32_16x16x32_bf16 v[102:105], v[240:243], v[184:187], v[102:105]
	v_mfma_f32_16x16x32_bf16 v[98:101], v[244:247], v[184:187], v[98:101]
	v_mfma_f32_16x16x32_bf16 v[94:97], v[232:235], v[188:191], v[94:97]
	v_mfma_f32_16x16x32_bf16 v[90:93], v[236:239], v[188:191], v[90:93]
	v_mfma_f32_16x16x32_bf16 v[86:89], v[240:243], v[188:191], v[86:89]
	v_mfma_f32_16x16x32_bf16 v[82:85], v[244:247], v[188:191], v[82:85]
	v_mfma_f32_16x16x32_bf16 v[78:81], v[232:235], v[192:195], v[78:81]
	v_mfma_f32_16x16x32_bf16 v[74:77], v[236:239], v[192:195], v[74:77]
	v_mfma_f32_16x16x32_bf16 v[70:73], v[240:243], v[192:195], v[70:73]
	v_mfma_f32_16x16x32_bf16 v[66:69], v[244:247], v[192:195], v[66:69]
	s_waitcnt vmcnt(0)
	s_waitcnt lgkmcnt(0)
	s_barrier
	s_add_u32 s8, s8, 0x80
	s_addc_u32 s9, s9, 0
	s_add_u32 s98, s98, 0x80
	s_addc_u32 s99, s99, 0
	s_add_u32 s100, s100, 0x80
	s_addc_u32 s101, s101, 0
	s_cmpk_eq_i32 s8, 0x780
	s_cbranch_scc1 .Lg2_p12_tail
	ds_read_b128 v[180:183], v148 offset:32768
	ds_read_b128 v[184:187], v148 offset:34816
	ds_read_b128 v[188:191], v148 offset:36864
	ds_read_b128 v[192:195], v148 offset:38912
	ds_read_b128 v[212:215], v149 offset:32768
	ds_read_b128 v[218:221], v149 offset:34816
	ds_read_b128 v[224:227], v149 offset:36864
	ds_read_b128 v[228:231], v149 offset:38912
	v_mfma_f32_16x16x32_bf16 v[62:65], v[232:235], v[196:199], v[62:65]
	s_mov_b32 m0, s96
	s_nop 0
	v_mfma_f32_16x16x32_bf16 v[58:61], v[236:239], v[196:199], v[58:61]
	global_load_lds_dwordx4 v140, s[98:99]
	v_mfma_f32_16x16x32_bf16 v[54:57], v[240:243], v[196:199], v[54:57]
	s_add_u32 m0, m0, 0x2000
	v_mfma_f32_16x16x32_bf16 v[50:53], v[244:247], v[196:199], v[50:53]
	global_load_lds_dwordx4 v152, s[98:99]
	v_mfma_f32_16x16x32_bf16 v[46:49], v[232:235], v[200:203], v[46:49]
	s_add_u32 m0, m0, 0x2000
	v_mfma_f32_16x16x32_bf16 v[42:45], v[236:239], v[200:203], v[42:45]
	global_load_lds_dwordx4 v156, s[98:99]
	v_mfma_f32_16x16x32_bf16 v[38:41], v[240:243], v[200:203], v[38:41]
	s_add_u32 m0, m0, 0x2000
	v_mfma_f32_16x16x32_bf16 v[34:37], v[244:247], v[200:203], v[34:37]
	global_load_lds_dwordx4 v160, s[98:99]
	v_mfma_f32_16x16x32_bf16 v[30:33], v[232:235], v[204:207], v[30:33]
	s_add_u32 m0, m0, 0xa000
	v_mfma_f32_16x16x32_bf16 v[26:29], v[236:239], v[204:207], v[26:29]
	global_load_lds_dwordx4 v164, s[100:101]
	v_mfma_f32_16x16x32_bf16 v[22:25], v[240:243], v[204:207], v[22:25]
	s_add_u32 m0, m0, 0x2000
	v_mfma_f32_16x16x32_bf16 v[18:21], v[244:247], v[204:207], v[18:21]
	global_load_lds_dwordx4 v168, s[100:101]
	v_mfma_f32_16x16x32_bf16 v[14:17], v[232:235], v[208:211], v[14:17]
	s_add_u32 m0, m0, 0x2000
	v_mfma_f32_16x16x32_bf16 v[10:13], v[236:239], v[208:211], v[10:13]
	global_load_lds_dwordx4 v172, s[100:101]
	v_mfma_f32_16x16x32_bf16 v[6:9], v[240:243], v[208:211], v[6:9]
	s_add_u32 m0, m0, 0x2000
	v_mfma_f32_16x16x32_bf16 v[2:5], v[244:247], v[208:211], v[2:5]
	global_load_lds_dwordx4 v176, s[100:101]
	ds_read_b128 v[196:199], v148 offset:40960
	ds_read_b128 v[200:203], v148 offset:43008
	ds_read_b128 v[204:207], v148 offset:45056
	ds_read_b128 v[208:211], v148 offset:47104
	s_waitcnt lgkmcnt(4)
	s_nop 0
	v_mfma_f32_16x16x32_bf16 v[126:129], v[212:215], v[180:183], v[126:129]
	v_mfma_f32_16x16x32_bf16 v[122:125], v[218:221], v[180:183], v[122:125]
	v_mfma_f32_16x16x32_bf16 v[118:121], v[224:227], v[180:183], v[118:121]
	v_mfma_f32_16x16x32_bf16 v[114:117], v[228:231], v[180:183], v[114:117]
	v_mfma_f32_16x16x32_bf16 v[110:113], v[212:215], v[184:187], v[110:113]
	v_mfma_f32_16x16x32_bf16 v[106:109], v[218:221], v[184:187], v[106:109]
	v_mfma_f32_16x16x32_bf16 v[102:105], v[224:227], v[184:187], v[102:105]
	v_mfma_f32_16x16x32_bf16 v[98:101], v[228:231], v[184:187], v[98:101]
	v_mfma_f32_16x16x32_bf16 v[94:97], v[212:215], v[188:191], v[94:97]
	v_mfma_f32_16x16x32_bf16 v[90:93], v[218:221], v[188:191], v[90:93]
	v_mfma_f32_16x16x32_bf16 v[86:89], v[224:227], v[188:191], v[86:89]
	v_mfma_f32_16x16x32_bf16 v[82:85], v[228:231], v[188:191], v[82:85]
	v_mfma_f32_16x16x32_bf16 v[78:81], v[212:215], v[192:195], v[78:81]
	v_mfma_f32_16x16x32_bf16 v[74:77], v[218:221], v[192:195], v[74:77]
	v_mfma_f32_16x16x32_bf16 v[70:73], v[224:227], v[192:195], v[70:73]
	v_mfma_f32_16x16x32_bf16 v[66:69], v[228:231], v[192:195], v[66:69]
	ds_read_b128 v[180:183], v216 offset:32768
	ds_read_b128 v[184:187], v216 offset:34816
	ds_read_b128 v[188:191], v216 offset:36864
	ds_read_b128 v[192:195], v216 offset:38912
	ds_read_b128 v[232:235], v217 offset:32768
	ds_read_b128 v[236:239], v217 offset:34816
	ds_read_b128 v[240:243], v217 offset:36864
	ds_read_b128 v[244:247], v217 offset:38912
	s_waitcnt lgkmcnt(8)
	s_nop 0
	v_mfma_f32_16x16x32_bf16 v[62:65], v[212:215], v[196:199], v[62:65]
	v_mfma_f32_16x16x32_bf16 v[58:61], v[218:221], v[196:199], v[58:61]
	v_mfma_f32_16x16x32_bf16 v[54:57], v[224:227], v[196:199], v[54:57]
	v_mfma_f32_16x16x32_bf16 v[50:53], v[228:231], v[196:199], v[50:53]
	v_mfma_f32_16x16x32_bf16 v[46:49], v[212:215], v[200:203], v[46:49]
	v_mfma_f32_16x16x32_bf16 v[42:45], v[218:221], v[200:203], v[42:45]
	v_mfma_f32_16x16x32_bf16 v[38:41], v[224:227], v[200:203], v[38:41]
	v_mfma_f32_16x16x32_bf16 v[34:37], v[228:231], v[200:203], v[34:37]
	v_mfma_f32_16x16x32_bf16 v[30:33], v[212:215], v[204:207], v[30:33]
	v_mfma_f32_16x16x32_bf16 v[26:29], v[218:221], v[204:207], v[26:29]
	v_mfma_f32_16x16x32_bf16 v[22:25], v[224:227], v[204:207], v[22:25]
	v_mfma_f32_16x16x32_bf16 v[18:21], v[228:231], v[204:207], v[18:21]
	v_mfma_f32_16x16x32_bf16 v[14:17], v[212:215], v[208:211], v[14:17]
	v_mfma_f32_16x16x32_bf16 v[10:13], v[218:221], v[208:211], v[10:13]
	v_mfma_f32_16x16x32_bf16 v[6:9], v[224:227], v[208:211], v[6:9]
	v_mfma_f32_16x16x32_bf16 v[2:5], v[228:231], v[208:211], v[2:5]
	ds_read_b128 v[196:199], v216 offset:40960
	ds_read_b128 v[200:203], v216 offset:43008
	ds_read_b128 v[204:207], v216 offset:45056
	ds_read_b128 v[208:211], v216 offset:47104
	s_waitcnt lgkmcnt(4)
	s_nop 0
	v_mfma_f32_16x16x32_bf16 v[126:129], v[232:235], v[180:183], v[126:129]
	v_mfma_f32_16x16x32_bf16 v[122:125], v[236:239], v[180:183], v[122:125]
	v_mfma_f32_16x16x32_bf16 v[118:121], v[240:243], v[180:183], v[118:121]
	v_mfma_f32_16x16x32_bf16 v[114:117], v[244:247], v[180:183], v[114:117]
	v_mfma_f32_16x16x32_bf16 v[110:113], v[232:235], v[184:187], v[110:113]
	v_mfma_f32_16x16x32_bf16 v[106:109], v[236:239], v[184:187], v[106:109]
	v_mfma_f32_16x16x32_bf16 v[102:105], v[240:243], v[184:187], v[102:105]
	v_mfma_f32_16x16x32_bf16 v[98:101], v[244:247], v[184:187], v[98:101]
	v_mfma_f32_16x16x32_bf16 v[94:97], v[232:235], v[188:191], v[94:97]
	v_mfma_f32_16x16x32_bf16 v[90:93], v[236:239], v[188:191], v[90:93]
	v_mfma_f32_16x16x32_bf16 v[86:89], v[240:243], v[188:191], v[86:89]
	v_mfma_f32_16x16x32_bf16 v[82:85], v[244:247], v[188:191], v[82:85]
	v_mfma_f32_16x16x32_bf16 v[78:81], v[232:235], v[192:195], v[78:81]
	v_mfma_f32_16x16x32_bf16 v[74:77], v[236:239], v[192:195], v[74:77]
	v_mfma_f32_16x16x32_bf16 v[70:73], v[240:243], v[192:195], v[70:73]
	v_mfma_f32_16x16x32_bf16 v[66:69], v[244:247], v[192:195], v[66:69]
	s_waitcnt vmcnt(0)
	s_waitcnt lgkmcnt(0)
	s_barrier
	s_add_u32 s8, s8, 0x80
	s_addc_u32 s9, s9, 0
	s_add_u32 s98, s98, 0x80
	s_addc_u32 s99, s99, 0
	s_add_u32 s100, s100, 0x80
	s_addc_u32 s101, s101, 0
	s_cmpk_eq_i32 s8, 0x780
	s_cbranch_scc1 .Lg2_p12_tail
	ds_read_b128 v[180:183], v148
	ds_read_b128 v[184:187], v148 offset:2048
	ds_read_b128 v[188:191], v148 offset:4096
	ds_read_b128 v[192:195], v148 offset:6144
	ds_read_b128 v[212:215], v149
	ds_read_b128 v[218:221], v149 offset:2048
	ds_read_b128 v[224:227], v149 offset:4096
	ds_read_b128 v[228:231], v149 offset:6144
	v_mfma_f32_16x16x32_bf16 v[62:65], v[232:235], v[196:199], v[62:65]
	s_add_u32 m0, s96, 0x8000
	v_mfma_f32_16x16x32_bf16 v[58:61], v[236:239], v[196:199], v[58:61]
	global_load_lds_dwordx4 v140, s[98:99]
	v_mfma_f32_16x16x32_bf16 v[54:57], v[240:243], v[196:199], v[54:57]
	s_add_u32 m0, m0, 0x2000
	v_mfma_f32_16x16x32_bf16 v[50:53], v[244:247], v[196:199], v[50:53]
	global_load_lds_dwordx4 v152, s[98:99]
	v_mfma_f32_16x16x32_bf16 v[46:49], v[232:235], v[200:203], v[46:49]
	s_add_u32 m0, m0, 0x2000
	v_mfma_f32_16x16x32_bf16 v[42:45], v[236:239], v[200:203], v[42:45]
	global_load_lds_dwordx4 v156, s[98:99]
	v_mfma_f32_16x16x32_bf16 v[38:41], v[240:243], v[200:203], v[38:41]
	s_add_u32 m0, m0, 0x2000
	v_mfma_f32_16x16x32_bf16 v[34:37], v[244:247], v[200:203], v[34:37]
	global_load_lds_dwordx4 v160, s[98:99]
	v_mfma_f32_16x16x32_bf16 v[30:33], v[232:235], v[204:207], v[30:33]
	s_add_u32 m0, m0, 0xa000
	v_mfma_f32_16x16x32_bf16 v[26:29], v[236:239], v[204:207], v[26:29]
	global_load_lds_dwordx4 v164, s[100:101]
	v_mfma_f32_16x16x32_bf16 v[22:25], v[240:243], v[204:207], v[22:25]
	s_add_u32 m0, m0, 0x2000
	v_mfma_f32_16x16x32_bf16 v[18:21], v[244:247], v[204:207], v[18:21]
	global_load_lds_dwordx4 v168, s[100:101]
	v_mfma_f32_16x16x32_bf16 v[14:17], v[232:235], v[208:211], v[14:17]
	s_add_u32 m0, m0, 0x2000
	v_mfma_f32_16x16x32_bf16 v[10:13], v[236:239], v[208:211], v[10:13]
	global_load_lds_dwordx4 v172, s[100:101]
	v_mfma_f32_16x16x32_bf16 v[6:9], v[240:243], v[208:211], v[6:9]
	s_add_u32 m0, m0, 0x2000
	v_mfma_f32_16x16x32_bf16 v[2:5], v[244:247], v[208:211], v[2:5]
	global_load_lds_dwordx4 v176, s[100:101]
	s_branch .Lg2_p12_loop
